# v42 + V-fragment reads split: PV0-operand pair behind PV0 fillers, PV1-operand pair behind PV1 fillers (one LDS burst per MFMA shadow)
# speedup vs baseline: 1.0373x; 1.0028x over previous
.Latt_loop:
	s_add_i32 s13, s12, 1
	s_cmp_eq_u32 s12, 2
	s_cselect_b32 s12, 0, s13
	s_mul_i32 s15, s12, 0x4800
	s_mul_i32 s16, s12, 0x6000
	s_add_i32 s16, s16, 0xd800
	s_add_i32 s17, s14, 2
	s_min_u32 s17, s17, s11
	s_lshl_b32 s64, s17, 17
	s_add_u32 s18, s64, s83
	s_mov_b32 s19, 0
	s_add_i32 s14, s14, 1
	v_mov_b32_e32 v250, v251
	v_add3_u32 v251, s15, v236, v210
	v_mov_b32_e32 v252, v215
	v_add_u32_e32 v215, s16, v232
	s_waitcnt lgkmcnt(5)
	v_mfma_f32_32x32x16_bf16 v[98:113], v[238:241], v[134:137], 0
	v_exp_f32_e32 v66, v66
	v_exp_f32_e32 v67, v67
	v_exp_f32_e32 v68, v68
	ds_read_b128 v[238:241], v250 offset:4672
	v_mfma_f32_32x32x16_bf16 v[34:49], v[182:185], v[118:121], v[34:49]
	v_exp_f32_e32 v69, v69
	v_exp_f32_e32 v70, v70
	v_exp_f32_e32 v71, v71
	ds_read_b64_tr_b16 v[182:183], v252 offset:3072
	ds_read_b64_tr_b16 v[184:185], v252 offset:4608
	v_mfma_f32_32x32x16_bf16 v[50:65], v[186:189], v[118:121], v[50:65]
	v_exp_f32_e32 v72, v72
	v_exp_f32_e32 v73, v73
	v_cvt_pk_bf16_f32 v66, v66, v67
	v_cvt_pk_bf16_f32 v67, v68, v69
	ds_read_b64_tr_b16 v[186:187], v252 offset:3136
	ds_read_b64_tr_b16 v[188:189], v252 offset:4672
	v_mfma_f32_16x16x32_bf16 v[170:173], v[130:133], v[118:121], v[170:173]
	v_cvt_pk_bf16_f32 v68, v70, v71
	v_cvt_pk_bf16_f32 v69, v72, v73
	s_waitcnt vmcnt(0)
	v_add_u32_e32 v246, s15, v204
	v_add_u32_e32 v247, s16, v231
	ds_write_b128 v246, v[158:161]
	ds_write_b128 v246, v[162:165] offset:9216
	ds_write_b128 v247, v[150:153]
	ds_write_b128 v247, v[154:157] offset:12288
	s_add_u32 s18, s100, s64
	s_addc_u32 s19, s101, 0
	global_load_dwordx4 v[158:161], v248, s[18:19]
	global_load_dwordx4 v[162:165], v249, s[18:19]
	s_add_u32 s18, s18, 0x1040000
	s_addc_u32 s19, s19, 0
	global_load_dwordx4 v[150:153], v248, s[18:19]
	global_load_dwordx4 v[154:157], v249, s[18:19]
	s_waitcnt lgkmcnt(9)
	v_mfma_f32_32x32x16_bf16 v[98:113], v[242:245], v[138:141], v[98:113]
	v_exp_f32_e32 v82, v82
	v_exp_f32_e32 v83, v83
	v_exp_f32_e32 v84, v84
	ds_read_b128 v[242:245], v250 offset:4704
	v_mfma_f32_32x32x16_bf16 v[2:17], v[174:177], v[66:69], v[2:17]
	v_exp_f32_e32 v85, v85
	v_exp_f32_e32 v86, v86
	v_exp_f32_e32 v87, v87
	v_mfma_f32_32x32x16_bf16 v[18:33], v[178:181], v[66:69], v[18:33]
	v_exp_f32_e32 v88, v88
	v_exp_f32_e32 v89, v89
	v_cvt_pk_bf16_f32 v82, v82, v83
	v_cvt_pk_bf16_f32 v83, v84, v85
	v_mfma_f32_16x16x32_bf16 v[166:169], v[130:133], v[66:69], v[166:169]
	v_cvt_pk_bf16_f32 v84, v86, v87
	v_cvt_pk_bf16_f32 v85, v88, v89
	s_waitcnt lgkmcnt(9)
	v_mfma_f32_32x32x16_bf16 v[114:129], v[238:241], v[142:145], 0
	v_exp_f32_e32 v74, v74
	v_exp_f32_e32 v75, v75
	v_exp_f32_e32 v76, v76
	ds_read_b128 v[238:241], v250 offset:9216
	v_mfma_f32_32x32x16_bf16 v[34:49], v[174:177], v[82:85], v[34:49]
	v_exp_f32_e32 v77, v77
	v_exp_f32_e32 v78, v78
	v_exp_f32_e32 v79, v79
	ds_read_b64_tr_b16 v[174:175], v252 offset:6144
	ds_read_b64_tr_b16 v[176:177], v252 offset:7680
	v_mfma_f32_32x32x16_bf16 v[50:65], v[178:181], v[82:85], v[50:65]
	v_exp_f32_e32 v80, v80
	v_exp_f32_e32 v81, v81
	v_cvt_pk_bf16_f32 v70, v74, v75
	v_cvt_pk_bf16_f32 v71, v76, v77
	ds_read_b64_tr_b16 v[178:179], v252 offset:6208
	ds_read_b64_tr_b16 v[180:181], v252 offset:7744
	v_mfma_f32_16x16x32_bf16 v[170:173], v[130:133], v[82:85], v[170:173]
	v_cvt_pk_bf16_f32 v72, v78, v79
	v_cvt_pk_bf16_f32 v73, v80, v81
	s_waitcnt lgkmcnt(5)
	v_mfma_f32_32x32x16_bf16 v[114:129], v[242:245], v[146:149], v[114:129]
	v_exp_f32_e32 v90, v90
	v_exp_f32_e32 v91, v91
	v_exp_f32_e32 v92, v92
	ds_read_b128 v[242:245], v250 offset:9248
	v_mfma_f32_32x32x16_bf16 v[2:17], v[182:185], v[70:73], v[2:17]
	v_exp_f32_e32 v93, v93
	v_exp_f32_e32 v94, v94
	v_exp_f32_e32 v95, v95
	v_mfma_f32_32x32x16_bf16 v[18:33], v[186:189], v[70:73], v[18:33]
	v_exp_f32_e32 v96, v96
	v_exp_f32_e32 v97, v97
	v_cvt_pk_bf16_f32 v86, v90, v91
	v_cvt_pk_bf16_f32 v87, v92, v93
	v_mfma_f32_16x16x32_bf16 v[166:169], v[130:133], v[70:73], v[166:169]
	v_cvt_pk_bf16_f32 v88, v94, v95
	v_cvt_pk_bf16_f32 v89, v96, v97
	s_waitcnt lgkmcnt(5)
	v_mfma_f32_32x32x16_bf16 v[66:81], v[238:241], v[134:137], 0
	v_exp_f32_e32 v98, v98
	v_exp_f32_e32 v99, v99
	v_exp_f32_e32 v100, v100
	ds_read_b128 v[238:241], v250 offset:9280
	v_mfma_f32_32x32x16_bf16 v[34:49], v[182:185], v[86:89], v[34:49]
	v_exp_f32_e32 v101, v101
	v_exp_f32_e32 v102, v102
	v_exp_f32_e32 v103, v103
	ds_read_b64_tr_b16 v[182:183], v252 offset:9216
	ds_read_b64_tr_b16 v[184:185], v252 offset:10752
	v_mfma_f32_32x32x16_bf16 v[50:65], v[186:189], v[86:89], v[50:65]
	v_exp_f32_e32 v104, v104
	v_exp_f32_e32 v105, v105
	v_cvt_pk_bf16_f32 v98, v98, v99
	v_cvt_pk_bf16_f32 v99, v100, v101
	ds_read_b64_tr_b16 v[186:187], v252 offset:9280
	ds_read_b64_tr_b16 v[188:189], v252 offset:10816
	v_mfma_f32_16x16x32_bf16 v[170:173], v[130:133], v[86:89], v[170:173]
	v_cvt_pk_bf16_f32 v100, v102, v103
	v_cvt_pk_bf16_f32 v101, v104, v105
	s_waitcnt lgkmcnt(5)
	v_mfma_f32_32x32x16_bf16 v[66:81], v[242:245], v[138:141], v[66:81]
	v_exp_f32_e32 v114, v114
	v_exp_f32_e32 v115, v115
	v_exp_f32_e32 v116, v116
	ds_read_b128 v[242:245], v250 offset:9312
	v_mfma_f32_32x32x16_bf16 v[2:17], v[174:177], v[98:101], v[2:17]
	v_exp_f32_e32 v117, v117
	v_exp_f32_e32 v118, v118
	v_exp_f32_e32 v119, v119
	v_mfma_f32_32x32x16_bf16 v[18:33], v[178:181], v[98:101], v[18:33]
	v_exp_f32_e32 v120, v120
	v_exp_f32_e32 v121, v121
	v_cvt_pk_bf16_f32 v114, v114, v115
	v_cvt_pk_bf16_f32 v115, v116, v117
	v_mfma_f32_16x16x32_bf16 v[166:169], v[130:133], v[98:101], v[166:169]
	v_cvt_pk_bf16_f32 v116, v118, v119
	v_cvt_pk_bf16_f32 v117, v120, v121
	s_waitcnt lgkmcnt(5)
	v_mfma_f32_32x32x16_bf16 v[82:97], v[238:241], v[142:145], 0
	v_exp_f32_e32 v106, v106
	v_exp_f32_e32 v107, v107
	v_exp_f32_e32 v108, v108
	ds_read_b128 v[238:241], v250 offset:13824
	v_mfma_f32_32x32x16_bf16 v[34:49], v[174:177], v[114:117], v[34:49]
	v_exp_f32_e32 v109, v109
	v_exp_f32_e32 v110, v110
	v_exp_f32_e32 v111, v111
	ds_read_b64_tr_b16 v[174:175], v252 offset:12288
	ds_read_b64_tr_b16 v[176:177], v252 offset:13824
	v_mfma_f32_32x32x16_bf16 v[50:65], v[178:181], v[114:117], v[50:65]
	v_exp_f32_e32 v112, v112
	v_exp_f32_e32 v113, v113
	v_cvt_pk_bf16_f32 v102, v106, v107
	v_cvt_pk_bf16_f32 v103, v108, v109
	ds_read_b64_tr_b16 v[178:179], v252 offset:12352
	ds_read_b64_tr_b16 v[180:181], v252 offset:13888
	v_mfma_f32_16x16x32_bf16 v[170:173], v[130:133], v[114:117], v[170:173]
	v_cvt_pk_bf16_f32 v104, v110, v111
	v_cvt_pk_bf16_f32 v105, v112, v113
	s_waitcnt lgkmcnt(5)
	v_mfma_f32_32x32x16_bf16 v[82:97], v[242:245], v[146:149], v[82:97]
	v_exp_f32_e32 v122, v122
	v_exp_f32_e32 v123, v123
	v_exp_f32_e32 v124, v124
	ds_read_b128 v[242:245], v250 offset:13856
	v_mfma_f32_32x32x16_bf16 v[2:17], v[182:185], v[102:105], v[2:17]
	v_exp_f32_e32 v125, v125
	v_exp_f32_e32 v126, v126
	v_exp_f32_e32 v127, v127
	v_mfma_f32_32x32x16_bf16 v[18:33], v[186:189], v[102:105], v[18:33]
	v_exp_f32_e32 v128, v128
	v_exp_f32_e32 v129, v129
	v_cvt_pk_bf16_f32 v118, v122, v123
	v_cvt_pk_bf16_f32 v119, v124, v125
	v_mfma_f32_16x16x32_bf16 v[166:169], v[130:133], v[102:105], v[166:169]
	v_cvt_pk_bf16_f32 v120, v126, v127
	v_cvt_pk_bf16_f32 v121, v128, v129
	s_waitcnt lgkmcnt(5)
	v_mfma_f32_32x32x16_bf16 v[98:113], v[238:241], v[134:137], 0
	v_exp_f32_e32 v66, v66
	v_exp_f32_e32 v67, v67
	v_exp_f32_e32 v68, v68
	ds_read_b128 v[238:241], v250 offset:13888
	v_mfma_f32_32x32x16_bf16 v[34:49], v[182:185], v[118:121], v[34:49]
	v_exp_f32_e32 v69, v69
	v_exp_f32_e32 v70, v70
	v_exp_f32_e32 v71, v71
	ds_read_b64_tr_b16 v[182:183], v252 offset:15360
	ds_read_b64_tr_b16 v[184:185], v252 offset:16896
	v_mfma_f32_32x32x16_bf16 v[50:65], v[186:189], v[118:121], v[50:65]
	v_exp_f32_e32 v72, v72
	v_exp_f32_e32 v73, v73
	v_cvt_pk_bf16_f32 v66, v66, v67
	v_cvt_pk_bf16_f32 v67, v68, v69
	ds_read_b64_tr_b16 v[186:187], v252 offset:15424
	ds_read_b64_tr_b16 v[188:189], v252 offset:16960
	v_mfma_f32_16x16x32_bf16 v[170:173], v[130:133], v[118:121], v[170:173]
	v_cvt_pk_bf16_f32 v68, v70, v71
	v_cvt_pk_bf16_f32 v69, v72, v73
	s_waitcnt lgkmcnt(5)
	v_mfma_f32_32x32x16_bf16 v[98:113], v[242:245], v[138:141], v[98:113]
	v_exp_f32_e32 v82, v82
	v_exp_f32_e32 v83, v83
	v_exp_f32_e32 v84, v84
	ds_read_b128 v[242:245], v250 offset:13920
	v_mfma_f32_32x32x16_bf16 v[2:17], v[174:177], v[66:69], v[2:17]
	v_exp_f32_e32 v85, v85
	v_exp_f32_e32 v86, v86
	v_exp_f32_e32 v87, v87
	v_mfma_f32_32x32x16_bf16 v[18:33], v[178:181], v[66:69], v[18:33]
	v_exp_f32_e32 v88, v88
	v_exp_f32_e32 v89, v89
	v_cvt_pk_bf16_f32 v82, v82, v83
	v_cvt_pk_bf16_f32 v83, v84, v85
	v_mfma_f32_16x16x32_bf16 v[166:169], v[130:133], v[66:69], v[166:169]
	v_cvt_pk_bf16_f32 v84, v86, v87
	v_cvt_pk_bf16_f32 v85, v88, v89
	s_barrier
	s_waitcnt lgkmcnt(5)
	v_mfma_f32_32x32x16_bf16 v[114:129], v[238:241], v[142:145], 0
	v_exp_f32_e32 v74, v74
	v_exp_f32_e32 v75, v75
	v_exp_f32_e32 v76, v76
	ds_read_b128 v[238:241], v251
	v_mfma_f32_32x32x16_bf16 v[34:49], v[174:177], v[82:85], v[34:49]
	v_exp_f32_e32 v77, v77
	v_exp_f32_e32 v78, v78
	v_exp_f32_e32 v79, v79
	ds_read_b64_tr_b16 v[174:175], v252 offset:18432
	ds_read_b64_tr_b16 v[176:177], v252 offset:19968
	v_mfma_f32_32x32x16_bf16 v[50:65], v[178:181], v[82:85], v[50:65]
	v_exp_f32_e32 v80, v80
	v_exp_f32_e32 v81, v81
	v_cvt_pk_bf16_f32 v70, v74, v75
	v_cvt_pk_bf16_f32 v71, v76, v77
	ds_read_b64_tr_b16 v[178:179], v252 offset:18496
	ds_read_b64_tr_b16 v[180:181], v252 offset:20032
	v_mfma_f32_16x16x32_bf16 v[170:173], v[130:133], v[82:85], v[170:173]
	v_cvt_pk_bf16_f32 v72, v78, v79
	v_cvt_pk_bf16_f32 v73, v80, v81
	s_waitcnt lgkmcnt(5)
	v_mfma_f32_32x32x16_bf16 v[114:129], v[242:245], v[146:149], v[114:129]
	v_exp_f32_e32 v90, v90
	v_exp_f32_e32 v91, v91
	v_exp_f32_e32 v92, v92
	ds_read_b128 v[242:245], v251 offset:32
	v_mfma_f32_32x32x16_bf16 v[2:17], v[182:185], v[70:73], v[2:17]
	v_exp_f32_e32 v93, v93
	v_exp_f32_e32 v94, v94
	v_exp_f32_e32 v95, v95
	v_mfma_f32_32x32x16_bf16 v[18:33], v[186:189], v[70:73], v[18:33]
	v_exp_f32_e32 v96, v96
	v_exp_f32_e32 v97, v97
	v_cvt_pk_bf16_f32 v86, v90, v91
	v_cvt_pk_bf16_f32 v87, v92, v93
	v_mfma_f32_16x16x32_bf16 v[166:169], v[130:133], v[70:73], v[166:169]
	v_cvt_pk_bf16_f32 v88, v94, v95
	v_cvt_pk_bf16_f32 v89, v96, v97
	s_waitcnt lgkmcnt(5)
	v_mfma_f32_32x32x16_bf16 v[66:81], v[238:241], v[134:137], 0
	v_exp_f32_e32 v98, v98
	v_exp_f32_e32 v99, v99
	v_exp_f32_e32 v100, v100
	ds_read_b128 v[238:241], v251 offset:64
	v_mfma_f32_32x32x16_bf16 v[34:49], v[182:185], v[86:89], v[34:49]
	v_exp_f32_e32 v101, v101
	v_exp_f32_e32 v102, v102
	v_exp_f32_e32 v103, v103
	ds_read_b64_tr_b16 v[182:183], v252 offset:21504
	ds_read_b64_tr_b16 v[184:185], v252 offset:23040
	v_mfma_f32_32x32x16_bf16 v[50:65], v[186:189], v[86:89], v[50:65]
	v_exp_f32_e32 v104, v104
	v_exp_f32_e32 v105, v105
	v_cvt_pk_bf16_f32 v98, v98, v99
	v_cvt_pk_bf16_f32 v99, v100, v101
	ds_read_b64_tr_b16 v[186:187], v252 offset:21568
	ds_read_b64_tr_b16 v[188:189], v252 offset:23104
	v_mfma_f32_16x16x32_bf16 v[170:173], v[130:133], v[86:89], v[170:173]
	v_cvt_pk_bf16_f32 v100, v102, v103
	v_cvt_pk_bf16_f32 v101, v104, v105
	s_waitcnt lgkmcnt(5)
	v_mfma_f32_32x32x16_bf16 v[66:81], v[242:245], v[138:141], v[66:81]
	v_exp_f32_e32 v114, v114
	v_exp_f32_e32 v115, v115
	v_exp_f32_e32 v116, v116
	ds_read_b128 v[242:245], v251 offset:96
	v_mfma_f32_32x32x16_bf16 v[2:17], v[174:177], v[98:101], v[2:17]
	v_exp_f32_e32 v117, v117
	v_exp_f32_e32 v118, v118
	v_exp_f32_e32 v119, v119
	v_mfma_f32_32x32x16_bf16 v[18:33], v[178:181], v[98:101], v[18:33]
	v_exp_f32_e32 v120, v120
	v_exp_f32_e32 v121, v121
	v_cvt_pk_bf16_f32 v114, v114, v115
	v_cvt_pk_bf16_f32 v115, v116, v117
	v_mfma_f32_16x16x32_bf16 v[166:169], v[130:133], v[98:101], v[166:169]
	v_cvt_pk_bf16_f32 v116, v118, v119
	v_cvt_pk_bf16_f32 v117, v120, v121
	s_waitcnt lgkmcnt(5)
	v_mfma_f32_32x32x16_bf16 v[82:97], v[238:241], v[142:145], 0
	v_exp_f32_e32 v106, v106
	v_exp_f32_e32 v107, v107
	v_exp_f32_e32 v108, v108
	ds_read_b128 v[238:241], v251 offset:4608
	v_mfma_f32_32x32x16_bf16 v[34:49], v[174:177], v[114:117], v[34:49]
	v_exp_f32_e32 v109, v109
	v_exp_f32_e32 v110, v110
	v_exp_f32_e32 v111, v111
	ds_read_b64_tr_b16 v[174:175], v215
	ds_read_b64_tr_b16 v[176:177], v215 offset:1536
	v_mfma_f32_32x32x16_bf16 v[50:65], v[178:181], v[114:117], v[50:65]
	v_exp_f32_e32 v112, v112
	v_exp_f32_e32 v113, v113
	v_cvt_pk_bf16_f32 v102, v106, v107
	v_cvt_pk_bf16_f32 v103, v108, v109
	ds_read_b64_tr_b16 v[178:179], v215 offset:64
	ds_read_b64_tr_b16 v[180:181], v215 offset:1600
	v_mfma_f32_16x16x32_bf16 v[170:173], v[130:133], v[114:117], v[170:173]
	v_cvt_pk_bf16_f32 v104, v110, v111
	v_cvt_pk_bf16_f32 v105, v112, v113
	s_waitcnt lgkmcnt(5)
	v_mfma_f32_32x32x16_bf16 v[82:97], v[242:245], v[146:149], v[82:97]
	v_exp_f32_e32 v122, v122
	v_exp_f32_e32 v123, v123
	v_exp_f32_e32 v124, v124
	ds_read_b128 v[242:245], v251 offset:4640
	v_mfma_f32_32x32x16_bf16 v[2:17], v[182:185], v[102:105], v[2:17]
	v_exp_f32_e32 v125, v125
	v_exp_f32_e32 v126, v126
	v_exp_f32_e32 v127, v127
	v_mfma_f32_32x32x16_bf16 v[18:33], v[186:189], v[102:105], v[18:33]
	v_exp_f32_e32 v128, v128
	v_exp_f32_e32 v129, v129
	v_cvt_pk_bf16_f32 v118, v122, v123
	v_cvt_pk_bf16_f32 v119, v124, v125
	v_mfma_f32_16x16x32_bf16 v[166:169], v[130:133], v[102:105], v[166:169]
	v_cvt_pk_bf16_f32 v120, v126, v127
	v_cvt_pk_bf16_f32 v121, v128, v129
	s_cmp_lg_u32 s14, s10
	s_cbranch_scc1 .Latt_loop
	s_waitcnt lgkmcnt(0)
	s_nop 1
	v_mfma_f32_16x16x32_bf16 v[170:173], v[130:133], v[118:121], v[170:173]
	v_mfma_f32_32x32x16_bf16 v[34:49], v[182:185], v[118:121], v[34:49]
	v_mfma_f32_32x32x16_bf16 v[50:65], v[186:189], v[118:121], v[50:65]
	s_nop 11
	global_load_dwordx4 v[98:101], v[212:213], off offset:32
	global_load_dwordx4 v[102:105], v[212:213], off offset:64
	global_load_dwordx4 v[106:109], v[212:213], off offset:96
	global_load_dwordx4 v[110:113], v[212:213], off offset:128
	global_load_dwordx4 v[114:117], v[212:213], off offset:160
	global_load_dwordx4 v[122:125], v[212:213], off offset:192
	global_load_dwordx4 v[126:129], v[212:213], off offset:224
	ds_bpermute_b32 v66, v237, v166
	s_nop 3
	ds_bpermute_b32 v67, v237, v170
	s_lshl_b32 s64, s9, 1
	v_mov_b32_e32 v215, v191
	s_mov_b32 s2, 0xf226000
	s_waitcnt lgkmcnt(1)
	v_div_scale_f32 v68, s[10:11], v66, v66, 1.0
	v_rcp_f32_e32 v69, v68
	s_add_i32 s8, s8, 1
	s_cmp_eq_u32 s8, s7
	v_fma_f32 v70, -v68, v69, 1.0
	v_fmac_f32_e32 v69, v70, v69
	v_div_scale_f32 v70, vcc, 1.0, v66, 1.0
	v_mul_f32_e32 v71, v70, v69
	v_fma_f32 v72, -v68, v71, v70
	v_fmac_f32_e32 v71, v72, v69
	v_fma_f32 v68, -v68, v71, v70
	v_div_fmas_f32 v68, v68, v69, v71
	v_div_fixup_f32 v66, v68, v66, 1.0
	s_waitcnt lgkmcnt(0)
	v_div_scale_f32 v68, s[10:11], v67, v67, v230
	v_rcp_f32_e32 v69, v68
	s_mov_b64 s[10:11], 0xf226400
	v_fma_f32 v70, -v68, v69, 1.0
	v_fmac_f32_e32 v69, v70, v69
	v_div_scale_f32 v70, vcc, v230, v67, v230
	v_mul_f32_e32 v71, v70, v69
	v_fma_f32 v72, -v68, v71, v70
	v_fmac_f32_e32 v71, v72, v69
	v_fma_f32 v68, -v68, v71, v70
	v_div_fmas_f32 v68, v68, v69, v71
	v_div_fixup_f32 v68, v68, v67, v230
	v_pk_mul_f32 v[62:63], v[62:63], v[68:69] op_sel_hi:[1,0]
	v_pk_mul_f32 v[34:35], v[34:35], v[68:69] op_sel_hi:[1,0]
	v_pk_fma_f32 v[30:31], v[30:31], v[66:67], v[62:63] op_sel_hi:[1,0,1] neg_lo:[0,0,1] neg_hi:[0,0,1]
	v_pk_mul_f32 v[62:63], v[64:65], v[68:69] op_sel_hi:[1,0]
	v_pk_mul_f32 v[36:37], v[36:37], v[68:69] op_sel_hi:[1,0]
	v_pk_fma_f32 v[32:33], v[32:33], v[66:67], v[62:63] op_sel_hi:[1,0,1] neg_lo:[0,0,1] neg_hi:[0,0,1]
	v_lshlrev_b64 v[62:63], 11, v[216:217]
	v_lshl_add_u64 v[62:63], s[54:55], 0, v[62:63]
	v_lshl_add_u64 v[74:75], v[62:63], 0, s[64:65]
	global_load_dwordx4 v[62:65], v[212:213], off
	v_pk_fma_f32 v[34:35], v[2:3], v[66:67], v[34:35] op_sel_hi:[1,0,1] neg_lo:[0,0,1] neg_hi:[0,0,1]
	v_pk_fma_f32 v[4:5], v[4:5], v[66:67], v[36:37] op_sel_hi:[1,0,1] neg_lo:[0,0,1] neg_hi:[0,0,1]
	v_pk_mul_f32 v[76:77], v[34:35], v[34:35]
	v_pk_mul_f32 v[40:41], v[40:41], v[68:69] op_sel_hi:[1,0]
	v_pk_mul_f32 v[38:39], v[38:39], v[68:69] op_sel_hi:[1,0]
	v_pk_mul_f32 v[44:45], v[44:45], v[68:69] op_sel_hi:[1,0]
	v_pk_mul_f32 v[42:43], v[42:43], v[68:69] op_sel_hi:[1,0]
	v_pk_mul_f32 v[48:49], v[48:49], v[68:69] op_sel_hi:[1,0]
	v_pk_mul_f32 v[46:47], v[46:47], v[68:69] op_sel_hi:[1,0]
	v_pk_mul_f32 v[52:53], v[52:53], v[68:69] op_sel_hi:[1,0]
	v_pk_mul_f32 v[50:51], v[50:51], v[68:69] op_sel_hi:[1,0]
	v_pk_mul_f32 v[56:57], v[56:57], v[68:69] op_sel_hi:[1,0]
	v_pk_mul_f32 v[54:55], v[54:55], v[68:69] op_sel_hi:[1,0]
	v_pk_mul_f32 v[60:61], v[60:61], v[68:69] op_sel_hi:[1,0]
	v_pk_mul_f32 v[58:59], v[58:59], v[68:69] op_sel_hi:[1,0]
	v_pk_mul_f32 v[36:37], v[4:5], v[4:5]
	v_pk_fma_f32 v[8:9], v[8:9], v[66:67], v[40:41] op_sel_hi:[1,0,1] neg_lo:[0,0,1] neg_hi:[0,0,1]
	v_pk_fma_f32 v[38:39], v[6:7], v[66:67], v[38:39] op_sel_hi:[1,0,1] neg_lo:[0,0,1] neg_hi:[0,0,1]
	v_pk_fma_f32 v[12:13], v[12:13], v[66:67], v[44:45] op_sel_hi:[1,0,1] neg_lo:[0,0,1] neg_hi:[0,0,1]
	v_pk_fma_f32 v[10:11], v[10:11], v[66:67], v[42:43] op_sel_hi:[1,0,1] neg_lo:[0,0,1] neg_hi:[0,0,1]
	v_pk_fma_f32 v[16:17], v[16:17], v[66:67], v[48:49] op_sel_hi:[1,0,1] neg_lo:[0,0,1] neg_hi:[0,0,1]
	v_pk_fma_f32 v[14:15], v[14:15], v[66:67], v[46:47] op_sel_hi:[1,0,1] neg_lo:[0,0,1] neg_hi:[0,0,1]
	v_pk_fma_f32 v[20:21], v[20:21], v[66:67], v[52:53] op_sel_hi:[1,0,1] neg_lo:[0,0,1] neg_hi:[0,0,1]
	v_pk_fma_f32 v[18:19], v[18:19], v[66:67], v[50:51] op_sel_hi:[1,0,1] neg_lo:[0,0,1] neg_hi:[0,0,1]
	v_pk_fma_f32 v[24:25], v[24:25], v[66:67], v[56:57] op_sel_hi:[1,0,1] neg_lo:[0,0,1] neg_hi:[0,0,1]
	v_pk_fma_f32 v[22:23], v[22:23], v[66:67], v[54:55] op_sel_hi:[1,0,1] neg_lo:[0,0,1] neg_hi:[0,0,1]
	v_pk_fma_f32 v[28:29], v[28:29], v[66:67], v[60:61] op_sel_hi:[1,0,1] neg_lo:[0,0,1] neg_hi:[0,0,1]
	v_pk_fma_f32 v[26:27], v[26:27], v[66:67], v[58:59] op_sel_hi:[1,0,1] neg_lo:[0,0,1] neg_hi:[0,0,1]
	v_add_f32_e32 v66, v76, v77
	v_add_f32_e32 v36, v36, v66
	v_pk_mul_f32 v[6:7], v[38:39], v[38:39]
	v_add_f32_e32 v36, v37, v36
	v_add_f32_e32 v6, v6, v36
	v_pk_mul_f32 v[40:41], v[8:9], v[8:9]
	v_add_f32_e32 v6, v7, v6
	v_add_f32_e32 v6, v40, v6
	v_pk_mul_f32 v[42:43], v[10:11], v[10:11]
	v_add_f32_e32 v6, v41, v6
	v_add_f32_e32 v6, v42, v6
	v_pk_mul_f32 v[44:45], v[12:13], v[12:13]
	v_add_f32_e32 v6, v43, v6
	v_add_f32_e32 v6, v44, v6
	v_pk_mul_f32 v[46:47], v[14:15], v[14:15]
	v_add_f32_e32 v6, v45, v6
	v_add_f32_e32 v6, v46, v6
	v_pk_mul_f32 v[48:49], v[16:17], v[16:17]
	v_add_f32_e32 v6, v47, v6
	v_add_f32_e32 v6, v48, v6
	v_pk_mul_f32 v[50:51], v[18:19], v[18:19]
	v_add_f32_e32 v6, v49, v6
	v_add_f32_e32 v6, v50, v6
	v_pk_mul_f32 v[52:53], v[20:21], v[20:21]
	v_add_f32_e32 v6, v51, v6
	v_add_f32_e32 v6, v52, v6
	v_pk_mul_f32 v[54:55], v[22:23], v[22:23]
	v_add_f32_e32 v6, v53, v6
	v_add_f32_e32 v6, v54, v6
	v_pk_mul_f32 v[56:57], v[24:25], v[24:25]
	v_add_f32_e32 v6, v55, v6
	v_add_f32_e32 v6, v56, v6
	v_pk_mul_f32 v[58:59], v[26:27], v[26:27]
	v_add_f32_e32 v6, v57, v6
	v_add_f32_e32 v6, v58, v6
	v_pk_mul_f32 v[60:61], v[28:29], v[28:29]
	v_add_f32_e32 v6, v59, v6
	v_add_f32_e32 v6, v60, v6
	v_pk_mul_f32 v[70:71], v[30:31], v[30:31]
	v_add_f32_e32 v6, v61, v6
	v_add_f32_e32 v6, v70, v6
	v_pk_mul_f32 v[72:73], v[32:33], v[32:33]
	v_add_f32_e32 v6, v71, v6
	v_add_f32_e32 v6, v72, v6
	v_add_f32_e32 v6, v73, v6
	ds_bpermute_b32 v7, v229, v6
	v_lshl_add_u64 v[74:75], v[74:75], 0, v[214:215]
	v_lshl_add_u64 v[2:3], v[74:75], 0, s[10:11]
	s_waitcnt lgkmcnt(0)
	v_add_f32_e32 v6, v6, v7
	v_fmamk_f32 v6, v6, 0x3c800000, v192
	v_cmp_gt_f32_e32 vcc, s70, v6
	v_mul_f32_e32 v7, 0x4b800000, v6
	s_nop 0
	v_cndmask_b32_e32 v6, v6, v7, vcc
	v_rsq_f32_e32 v6, v6
	s_nop 0
	v_mul_f32_e32 v7, 0x45800000, v6
	v_cndmask_b32_e32 v6, v6, v7, vcc
	v_mul_f32_e32 v36, v233, v6
	v_pk_mul_f32 v[6:7], v[34:35], v[36:37] op_sel_hi:[1,0]
	v_pk_mul_f32 v[4:5], v[4:5], v[36:37] op_sel_hi:[1,0]
	s_waitcnt vmcnt(0)
	v_pk_mul_f32 v[6:7], v[62:63], v[6:7]
	v_pk_mul_f32 v[4:5], v[64:65], v[4:5]
	v_cvt_pk_bf16_f32 v6, v6, v7
	v_cvt_pk_bf16_f32 v7, v4, v5
	v_add_co_u32_e32 v4, vcc, s2, v74
	v_pk_mul_f32 v[34:35], v[38:39], v[36:37] op_sel_hi:[1,0]
	s_nop 0
	v_addc_co_u32_e32 v5, vcc, 0, v75, vcc
	global_store_dwordx2 v[4:5], v[6:7], off offset:1024
	v_pk_mul_f32 v[8:9], v[8:9], v[36:37] op_sel_hi:[1,0]
	v_mov_b64_e32 v[4:5], v[98:99]
	v_mov_b64_e32 v[6:7], v[100:101]
	v_pk_mul_f32 v[4:5], v[4:5], v[34:35]
	v_pk_mul_f32 v[6:7], v[6:7], v[8:9]
	v_cvt_pk_bf16_f32 v4, v4, v5
	v_cvt_pk_bf16_f32 v5, v6, v7
	global_store_dwordx2 v[2:3], v[4:5], off offset:16
	v_pk_mul_f32 v[8:9], v[10:11], v[36:37] op_sel_hi:[1,0]
	v_mov_b64_e32 v[4:5], v[102:103]
	v_mov_b64_e32 v[6:7], v[104:105]
	v_pk_mul_f32 v[4:5], v[4:5], v[8:9]
	v_pk_mul_f32 v[8:9], v[12:13], v[36:37] op_sel_hi:[1,0]
	v_cvt_pk_bf16_f32 v4, v4, v5
	v_pk_mul_f32 v[6:7], v[6:7], v[8:9]
	v_pk_mul_f32 v[8:9], v[14:15], v[36:37] op_sel_hi:[1,0]
	v_cvt_pk_bf16_f32 v5, v6, v7
	global_store_dwordx2 v[2:3], v[4:5], off offset:32
	v_mov_b64_e32 v[4:5], v[106:107]
	v_mov_b64_e32 v[6:7], v[108:109]
	v_pk_mul_f32 v[4:5], v[4:5], v[8:9]
	v_pk_mul_f32 v[8:9], v[16:17], v[36:37] op_sel_hi:[1,0]
	v_cvt_pk_bf16_f32 v4, v4, v5
	v_pk_mul_f32 v[6:7], v[6:7], v[8:9]
	v_pk_mul_f32 v[8:9], v[18:19], v[36:37] op_sel_hi:[1,0]
	v_cvt_pk_bf16_f32 v5, v6, v7
	global_store_dwordx2 v[2:3], v[4:5], off offset:48
	v_mov_b64_e32 v[4:5], v[110:111]
	v_mov_b64_e32 v[6:7], v[112:113]
	v_pk_mul_f32 v[4:5], v[4:5], v[8:9]
	v_pk_mul_f32 v[8:9], v[20:21], v[36:37] op_sel_hi:[1,0]
	v_cvt_pk_bf16_f32 v4, v4, v5
	v_pk_mul_f32 v[6:7], v[6:7], v[8:9]
	v_pk_mul_f32 v[8:9], v[22:23], v[36:37] op_sel_hi:[1,0]
	v_cvt_pk_bf16_f32 v5, v6, v7
	global_store_dwordx2 v[2:3], v[4:5], off offset:64
	v_mov_b64_e32 v[4:5], v[114:115]
	v_mov_b64_e32 v[6:7], v[116:117]
	v_pk_mul_f32 v[4:5], v[4:5], v[8:9]
	v_pk_mul_f32 v[8:9], v[24:25], v[36:37] op_sel_hi:[1,0]
	v_cvt_pk_bf16_f32 v4, v4, v5
	v_pk_mul_f32 v[6:7], v[6:7], v[8:9]
	v_pk_mul_f32 v[8:9], v[26:27], v[36:37] op_sel_hi:[1,0]
	v_cvt_pk_bf16_f32 v5, v6, v7
	global_store_dwordx2 v[2:3], v[4:5], off offset:80
	v_mov_b64_e32 v[4:5], v[122:123]
	v_mov_b64_e32 v[6:7], v[124:125]
	v_pk_mul_f32 v[4:5], v[4:5], v[8:9]
	v_pk_mul_f32 v[8:9], v[28:29], v[36:37] op_sel_hi:[1,0]
	v_cvt_pk_bf16_f32 v4, v4, v5
	v_pk_mul_f32 v[6:7], v[6:7], v[8:9]
	v_pk_mul_f32 v[8:9], v[30:31], v[36:37] op_sel_hi:[1,0]
	v_cvt_pk_bf16_f32 v5, v6, v7
	global_store_dwordx2 v[2:3], v[4:5], off offset:96
	v_mov_b64_e32 v[4:5], v[126:127]
	v_mov_b64_e32 v[6:7], v[128:129]
	v_pk_mul_f32 v[4:5], v[4:5], v[8:9]
	v_pk_mul_f32 v[8:9], v[32:33], v[36:37] op_sel_hi:[1,0]
	v_cvt_pk_bf16_f32 v4, v4, v5
	v_pk_mul_f32 v[6:7], v[6:7], v[8:9]
	s_nop 0
	v_cvt_pk_bf16_f32 v5, v6, v7
	global_store_dwordx2 v[2:3], v[4:5], off offset:112
	s_cbranch_scc0 .LBB0_745
